# stage-2 softplus: log(1+exp(-|z|)) argument is always in [1,2], so the expanded logf's denormal-input guard and inf pass-through select are removed (bit-identical results); on top of all12
# baseline (speedup 1.0000x reference)
; #define LAS __attribute__((address_space(3)))
; #define LBAR() asm volatile("s_waitcnt lgkmcnt(0)\n\ts_barrier" ::: "memory")
; __device__ __forceinline__ void rwkv_chunk_group(Frame& F, int bc, unsigned long long& tsub) {
;     ...
;         asm volatile("s_waitcnt vmcnt(0)" ::: "memory"); LBAR();
;         f32x4 aw[2], aa[2], ag[2];
; #pragma unroll
;         for (int q = 0; q < 2; ++q) { const int n0 = 16 * ((2 * w + q) & 3); aw[q] = Z4; aa[q] = Z4; ag[q] = Z4;
;             const LAS unsigned char* wp = L + L_LWA + (n0 + fr) * 128 + fq * 16; const LAS unsigned char* gp = L + L_LG + (n0 + fr) * 64 + fq * 16;
; #pragma unroll
;             for (int k = 0; k < 2; ++k) { aw[q] = __builtin_amdgcn_mfma_f32_16x16x32_bf16(xw[k], *(const LAS bf16x8*)(wp + k * 64), aw[q], 0, 0, 0); aa[q] = __builtin_amdgcn_mfma_f32_16x16x32_bf16(xa[k], *(const LAS bf16x8*)(wp + 8192 + k * 64), aa[q], 0, 0, 0); }
; #pragma unroll
;             for (int k = 0; k < 5; ++k) ag[q] = __builtin_amdgcn_mfma_f32_16x16x32_bf16(xg[k], *(const LAS bf16x8*)(gp + k * 4096), ag[q], 0, 0, 0);
;     ...
;         const float mur = mu[gc], muk = mu[512 + gc], muv = mu[1024 + gc];
;         const float w0 = (PRM + 2048)[gc], a0 = (PRM + 2560)[gc], k_k = (PRM + 3072)[gc], k_a = (PRM + 3584)[gc], r_k = (PRM + 4096)[gc];
.LBB0_1412:
	s_waitcnt vmcnt(8)
	v_perm_b32 v160, v203, v202, s5
	v_perm_b32 v161, v216, v215, s5
	v_perm_b32 v166, v204, v203, s5
	v_perm_b32 v167, v217, v216, s5
	v_perm_b32 v168, v206, v205, s5
	v_perm_b32 v169, v219, v218, s5
	v_perm_b32 v170, v212, v207, s5
	v_perm_b32 v171, v221, v220, s5
	v_perm_b32 v165, v214, v213, s5
	v_perm_b32 v172, v223, v222, s5
	v_readlane_b32 s98, v254, 2
	v_readlane_b32 s100, v254, 20
	v_readlane_b32 s101, v254, 21
	s_add_i32 s98, s98, s12
	s_lshl_b32 s98, s98, 6
	s_and_b32 s98, s98, 0x1c0
	v_add_lshl_u32 v238, v208, s98, 2
	v_mov_b32_e32 v239, 0
	s_nop 0
	v_lshl_add_u64 v[232:233], s[100:101], 0, v[238:239]
	s_mov_b64 s[100:101], 0x2000
	v_lshl_add_u64 v[234:235], v[232:233], 0, s[100:101]
	s_mov_b64 s[100:101], 0x3800
	v_lshl_add_u64 v[236:237], v[232:233], 0, s[100:101]
	global_load_dword v224, v[232:233], off
	global_load_dword v225, v[232:233], off offset:2048
	global_load_dword v226, v[234:235], off offset:-4096
	global_load_dword v227, v[234:235], off
	global_load_dword v228, v[234:235], off offset:2048
	global_load_dword v229, v[236:237], off offset:-2048
	global_load_dword v230, v[236:237], off
	global_load_dword v231, v[236:237], off offset:2048
	s_waitcnt lgkmcnt(0)
	s_barrier
	v_xor_b32_e32 v102, 64, v137
	v_xor_b32_e32 v103, 64, v139
	ds_read_b128 v[36:39], v137
	ds_read_b128 v[76:79], v139
	ds_read_b128 v[98:101], v102
	ds_read_b128 v[174:177], v103
	ds_read_b128 v[40:43], v137 offset:8192
	ds_read_b128 v[80:83], v139 offset:8192
	ds_read_b128 v[178:181], v102 offset:8192
	ds_read_b128 v[182:185], v103 offset:8192
	ds_read_b128 v[44:47], v138
	ds_read_b128 v[84:87], v140
	ds_read_b128 v[186:189], v138 offset:4096
	ds_read_b128 v[232:235], v140 offset:4096
	ds_read_b128 v[236:239], v138 offset:8192
	ds_read_b128 v[240:243], v140 offset:8192
	ds_read_b128 v[244:247], v138 offset:12288
	s_waitcnt lgkmcnt(14)
	v_mfma_f32_16x16x32_bf16 v[36:39], v[0:3], v[36:39], 0
	ds_read_b128 v[248:251], v140 offset:12288
	v_add_u32_e32 v52, s33, v111
	s_mov_b32 s68, s12
	s_waitcnt lgkmcnt(14)
	v_mfma_f32_16x16x32_bf16 v[76:79], v[0:3], v[76:79], 0
	ds_read_b128 v[88:91], v138 offset:16384
	v_readlane_b32 s12, v254, 2
	s_add_i32 s14, s68, s12
	s_waitcnt lgkmcnt(14)
	v_mfma_f32_16x16x32_bf16 v[36:39], v[4:7], v[98:101], v[36:39]
	ds_read_b128 v[98:101], v140 offset:16384
	s_lshl_b32 s14, s14, 6
	s_waitcnt lgkmcnt(14)
	v_mfma_f32_16x16x32_bf16 v[76:79], v[4:7], v[174:177], v[76:79]
	s_and_b32 s14, s14, 0x1c0
	s_waitcnt lgkmcnt(13)
	v_mfma_f32_16x16x32_bf16 v[40:43], v[8:11], v[40:43], 0
	s_add_i32 s66, s11, s14
	s_waitcnt lgkmcnt(12)
	v_mfma_f32_16x16x32_bf16 v[80:83], v[8:11], v[80:83], 0
	v_add_u32_e32 v191, s6, v125
	s_waitcnt lgkmcnt(11)
	v_mfma_f32_16x16x32_bf16 v[40:43], v[12:15], v[178:181], v[40:43]

; #define LAS __attribute__((address_space(3)))
; #define LBAR() asm volatile("s_waitcnt lgkmcnt(0)\n\ts_barrier" ::: "memory")
; __device__ __forceinline__ void rwkv_chunk_group(Frame& F, int bc, unsigned long long& tsub) {
;     ...
;             for (int k = 0; k < 2; ++k) { aw[q] = __builtin_amdgcn_mfma_f32_16x16x32_bf16(xw[k], *(const LAS bf16x8*)(wp + k * 64), aw[q], 0, 0, 0); aa[q] = __builtin_amdgcn_mfma_f32_16x16x32_bf16(xa[k], *(const LAS bf16x8*)(wp + 8192 + k * 64), aa[q], 0, 0, 0); }
; #pragma unroll
;             for (int k = 0; k < 5; ++k) ag[q] = __builtin_amdgcn_mfma_f32_16x16x32_bf16(xg[k], *(const LAS bf16x8*)(gp + k * 4096), ag[q], 0, 0, 0);
;         }
;         LBAR();
; #pragma unroll
;         for (int q = 0; q < 2; ++q) { const int tw = 2 * w + q, m0 = 16 * (tw >> 2), n0 = 16 * (tw & 3);
; #pragma unroll
;             for (int v = 0; v < 4; ++v) { const int t = m0 + 4 * fq + v, cc = n0 + fr;
;                 *(LAS float*)(L + L_WL + (t * 65 + cc) * 4) = aw[q][v]; *(LAS float*)(L + L_AL + (t * 65 + cc) * 4) = aa[q][v]; *(LAS float*)(L + L_GL + (t * 65 + cc) * 4) = ag[q][v]; } }
	s_waitcnt lgkmcnt(10)
	v_mfma_f32_16x16x32_bf16 v[80:83], v[12:15], v[182:185], v[80:83]
	s_mov_b32 s64, s12
	s_waitcnt lgkmcnt(9)
	v_mfma_f32_16x16x32_bf16 v[44:47], v[16:19], v[44:47], 0
	s_add_i32 s12, s68, 1
	s_waitcnt lgkmcnt(8)
	v_mfma_f32_16x16x32_bf16 v[84:87], v[16:19], v[84:87], 0
	s_add_i32 s13, s12, s64
	s_waitcnt lgkmcnt(7)
	v_mfma_f32_16x16x32_bf16 v[44:47], v[20:23], v[186:189], v[44:47]
	v_add_u32_e32 v96, s6, v124
	s_waitcnt lgkmcnt(6)
	v_mfma_f32_16x16x32_bf16 v[84:87], v[20:23], v[232:235], v[84:87]
	v_add_u32_e32 v93, s7, v123
	s_waitcnt lgkmcnt(5)
	v_mfma_f32_16x16x32_bf16 v[44:47], v[24:27], v[236:239], v[44:47]
	v_add_u32_e32 v97, s7, v124
	s_waitcnt lgkmcnt(4)
	v_mfma_f32_16x16x32_bf16 v[84:87], v[24:27], v[240:243], v[84:87]
	v_add_u32_e32 v192, s7, v125
	s_waitcnt lgkmcnt(3)
	v_mfma_f32_16x16x32_bf16 v[44:47], v[28:31], v[244:247], v[44:47]
	v_lshlrev_b32_e32 v197, 16, v162
	s_waitcnt lgkmcnt(2)
	v_mfma_f32_16x16x32_bf16 v[84:87], v[28:31], v[248:251], v[84:87]
	v_and_b32_e32 v199, 0xffff0000, v172
	s_waitcnt lgkmcnt(1)
	v_mfma_f32_16x16x32_bf16 v[44:47], v[32:35], v[88:91], v[44:47]
	s_ashr_i32 s67, s66, 31
	s_waitcnt lgkmcnt(0)
	v_mfma_f32_16x16x32_bf16 v[84:87], v[32:35], v[98:101], v[84:87]
	s_and_b32 s13, s13, 7
	s_nop 7
	s_nop 7
	s_waitcnt lgkmcnt(0)
	s_barrier
	ds_write_b32 v52, v36
	v_add_u32_e32 v36, s6, v111
	ds_write_b32 v36, v40
	v_add_u32_e32 v36, s7, v111
	ds_write_b32 v36, v44
	v_add_u32_e32 v36, s33, v112
	ds_write_b32 v36, v37
	v_add_u32_e32 v36, s6, v112
	ds_write_b32 v36, v41
	v_add_u32_e32 v36, s7, v112
	ds_write_b32 v36, v45
	v_add_u32_e32 v36, s33, v113
	ds_write_b32 v36, v38
	v_add_u32_e32 v36, s6, v113
	ds_write_b32 v36, v42
	v_add_u32_e32 v36, s7, v113
	ds_write_b32 v36, v46
	v_add_u32_e32 v36, s33, v114
	ds_write_b32 v36, v39
	v_add_u32_e32 v36, s6, v114
	ds_write_b32 v36, v43
	v_add_u32_e32 v36, s7, v114
	ds_write_b32 v36, v47
	v_add_u32_e32 v36, s33, v115
	ds_write_b32 v36, v76
	v_add_u32_e32 v36, s6, v115
	ds_write_b32 v36, v80
	v_add_u32_e32 v36, s7, v115
	ds_write_b32 v36, v84
	v_add_u32_e32 v36, s33, v116
	ds_write_b32 v36, v77
	v_add_u32_e32 v36, s6, v116
	ds_write_b32 v36, v81
	v_add_u32_e32 v36, s7, v116
	ds_write_b32 v36, v85
	v_add_u32_e32 v36, s33, v117
	ds_write_b32 v36, v78
	v_add_u32_e32 v36, s6, v117
	ds_write_b32 v36, v82
	v_add_u32_e32 v36, s7, v117
	ds_write_b32 v36, v86
	v_add_u32_e32 v36, s33, v118
	ds_write_b32 v36, v79
	v_add_u32_e32 v36, s6, v118
	ds_write_b32 v36, v83
	v_add_u32_e32 v36, s7, v118
	ds_write_b32 v36, v87


; #define LAS __attribute__((address_space(3)))
; #define LBAR() asm volatile("s_waitcnt lgkmcnt(0)\n\ts_barrier" ::: "memory")
; #define TSUB(k) do { } while (0)
; __device__ __forceinline__ void rwkv_chunk_group(Frame& F, int bc, unsigned long long& tsub) {
;     ...
;         LBAR();
;     }
;     TSUB(1);
;     {
;         const int gc = h * 64 + ch;
;         const float mur = mu[gc], muk = mu[512 + gc], muv = mu[1024 + gc];
;         const float w0 = (PRM + 2048)[gc], a0 = (PRM + 2560)[gc], k_k = (PRM + 3072)[gc], k_a = (PRM + 3584)[gc], r_k = (PRM + 4096)[gc];
;         float rr[8], kp[8], vv[8], aa[8], bb[8], ld[8], vbv[8], ggv[8];
;         float pr = bf2f(raw[0][0]), pk = bf2f(raw[0][1]), pv = bf2f(raw[0][2]);
;         bf16* VBp = (bf16*)(F.ws + WS_VB) + (size_t)item * 4096; bf16* Gp = (bf16*)(F.ws + WS_G) + (size_t)item * 4096;
;         float run = 0.f; float kkv[8], icv[8], sq[8], bq[8];
; #pragma unroll
;         for (int tt = 0; tt < 8; ++tt) { const int t = tb + tt;
;             const float cr = bf2f(raw[tt + 1][0]), ck = bf2f(raw[tt + 1][1]), cv = bf2f(raw[tt + 1][2]);
;             const float r = cr + (pr - cr) * mur, k = ck + (pk - ck) * muk, v = cv + (pv - cv) * muv; pr = cr; pk = ck; pv = cv;
;             const float wl = *(const LAS float*)(L + L_WL + (t * 65 + ch) * 4), al = *(const LAS float*)(L + L_AL + (t * 65 + ch) * 4), gl = *(const LAS float*)(L + L_GL + (t * 65 + ch) * 4);
	s_waitcnt lgkmcnt(0)
	s_barrier
	v_add_u32_e32 v41, s7, v120
	v_add_u32_e32 v87, s7, v122

; __device__ __forceinline__ void rwkv_chunk_group(Frame& F, int bc, unsigned long long& tsub) {
;     ...
;         const float mur = mu[gc], muk = mu[512 + gc], muv = mu[1024 + gc];
;         const float w0 = (PRM + 2048)[gc], a0 = (PRM + 2560)[gc], k_k = (PRM + 3072)[gc], k_a = (PRM + 3584)[gc], r_k = (PRM + 4096)[gc];
	s_waitcnt vmcnt(0)
	v_mov_b32_e32 v95, v224
	v_mov_b32_e32 v42, v225


; __device__ __forceinline__ void rwkv_chunk_group(Frame& F, int bc, unsigned long long& tsub) {
;     ...
;         const float mur = mu[gc], muk = mu[512 + gc], muv = mu[1024 + gc];
;         const float w0 = (PRM + 2048)[gc], a0 = (PRM + 2560)[gc], k_k = (PRM + 3072)[gc], k_a = (PRM + 3584)[gc], r_k = (PRM + 4096)[gc];
	s_nop 0


; #define LAS __attribute__((address_space(3)))
; __device__ __forceinline__ void rwkv_chunk_group(Frame& F, int bc, unsigned long long& tsub) {
;     ...
;         const float mur = mu[gc], muk = mu[512 + gc], muv = mu[1024 + gc];
;         const float w0 = (PRM + 2048)[gc], a0 = (PRM + 2560)[gc], k_k = (PRM + 3072)[gc], k_a = (PRM + 3584)[gc], r_k = (PRM + 4096)[gc];
;         float rr[8], kp[8], vv[8], aa[8], bb[8], ld[8], vbv[8], ggv[8];
;         float pr = bf2f(raw[0][0]), pk = bf2f(raw[0][1]), pv = bf2f(raw[0][2]);
;         bf16* VBp = (bf16*)(F.ws + WS_VB) + (size_t)item * 4096; bf16* Gp = (bf16*)(F.ws + WS_G) + (size_t)item * 4096;
;         float run = 0.f; float kkv[8], icv[8], sq[8], bq[8];
; #pragma unroll
;         for (int tt = 0; tt < 8; ++tt) { const int t = tb + tt;
;             const float cr = bf2f(raw[tt + 1][0]), ck = bf2f(raw[tt + 1][1]), cv = bf2f(raw[tt + 1][2]);
;             const float r = cr + (pr - cr) * mur, k = ck + (pk - ck) * muk, v = cv + (pv - cv) * muv; pr = cr; pk = ck; pv = cv;
;             const float wl = *(const LAS float*)(L + L_WL + (t * 65 + ch) * 4), al = *(const LAS float*)(L + L_AL + (t * 65 + ch) * 4), gl = *(const LAS float*)(L + L_GL + (t * 65 + ch) * 4);
	v_mov_b32_e32 v52, v226
	v_add_u32_e32 v83, s7, v121

; __device__ __forceinline__ void rwkv_chunk_group(Frame& F, int bc, unsigned long long& tsub) {
;     ...
;         const float mur = mu[gc], muk = mu[512 + gc], muv = mu[1024 + gc];
;         const float w0 = (PRM + 2048)[gc], a0 = (PRM + 2560)[gc], k_k = (PRM + 3072)[gc], k_a = (PRM + 3584)[gc], r_k = (PRM + 4096)[gc];
	v_mov_b32_e32 v45, v227


; __device__ __forceinline__ void rwkv_chunk_group(Frame& F, int bc, unsigned long long& tsub) {
;     ...
;             const float cr = bf2f(raw[tt + 1][0]), ck = bf2f(raw[tt + 1][1]), cv = bf2f(raw[tt + 1][2]);
;             const float r = cr + (pr - cr) * mur, k = ck + (pk - ck) * muk, v = cv + (pv - cv) * muv; pr = cr; pk = ck; pv = cv;
	v_lshlrev_b32_e32 v82, 16, v155
	v_and_b32_e32 v77, 0xffff0000, v167

; __device__ __forceinline__ void rwkv_chunk_group(Frame& F, int bc, unsigned long long& tsub) {
;     ...
;         const float mur = mu[gc], muk = mu[512 + gc], muv = mu[1024 + gc];
;         const float w0 = (PRM + 2048)[gc], a0 = (PRM + 2560)[gc], k_k = (PRM + 3072)[gc], k_a = (PRM + 3584)[gc], r_k = (PRM + 4096)[gc];
	v_mov_b32_e32 v43, v228


; __device__ __forceinline__ void rwkv_chunk_group(Frame& F, int bc, unsigned long long& tsub) {
;     ...
;             const float cr = bf2f(raw[tt + 1][0]), ck = bf2f(raw[tt + 1][1]), cv = bf2f(raw[tt + 1][2]);
;             const float r = cr + (pr - cr) * mur, k = ck + (pk - ck) * muk, v = cv + (pv - cv) * muv; pr = cr; pk = ck; pv = cv;
	v_lshlrev_b32_e32 v76, 16, v167
	v_and_b32_e32 v79, 0xffff0000, v166


; __device__ __forceinline__ void rwkv_chunk_group(Frame& F, int bc, unsigned long long& tsub) {
;     ...
;         const float mur = mu[gc], muk = mu[512 + gc], muv = mu[1024 + gc];
;         const float w0 = (PRM + 2048)[gc], a0 = (PRM + 2560)[gc], k_k = (PRM + 3072)[gc], k_a = (PRM + 3584)[gc], r_k = (PRM + 4096)[gc];
;         float rr[8], kp[8], vv[8], aa[8], bb[8], ld[8], vbv[8], ggv[8];
;         float pr = bf2f(raw[0][0]), pk = bf2f(raw[0][1]), pv = bf2f(raw[0][2]);
;         bf16* VBp = (bf16*)(F.ws + WS_VB) + (size_t)item * 4096; bf16* Gp = (bf16*)(F.ws + WS_G) + (size_t)item * 4096;
;         float run = 0.f; float kkv[8], icv[8], sq[8], bq[8];
; #pragma unroll
;         for (int tt = 0; tt < 8; ++tt) { const int t = tb + tt;
;             const float cr = bf2f(raw[tt + 1][0]), ck = bf2f(raw[tt + 1][1]), cv = bf2f(raw[tt + 1][2]);
;             const float r = cr + (pr - cr) * mur, k = ck + (pk - ck) * muk, v = cv + (pv - cv) * muv; pr = cr; pk = ck; pv = cv;
	v_mov_b32_e32 v44, v229
	v_lshlrev_b32_e32 v78, 16, v166

; __device__ __forceinline__ void rwkv_chunk_group(Frame& F, int bc, unsigned long long& tsub) {
;     ...
;         const float mur = mu[gc], muk = mu[512 + gc], muv = mu[1024 + gc];
;         const float w0 = (PRM + 2048)[gc], a0 = (PRM + 2560)[gc], k_k = (PRM + 3072)[gc], k_a = (PRM + 3584)[gc], r_k = (PRM + 4096)[gc];
	v_mov_b32_e32 v46, v230


; __device__ __forceinline__ void rwkv_chunk_group(Frame& F, int bc, unsigned long long& tsub) {
;     ...
;             const float cr = bf2f(raw[tt + 1][0]), ck = bf2f(raw[tt + 1][1]), cv = bf2f(raw[tt + 1][2]);
;             const float r = cr + (pr - cr) * mur, k = ck + (pk - ck) * muk, v = cv + (pv - cv) * muv; pr = cr; pk = ck; pv = cv;
	v_lshlrev_b32_e32 v86, 16, v157
	v_and_b32_e32 v91, 0xffff0000, v168

; #define LAS __attribute__((address_space(3)))
; __device__ __forceinline__ void rwkv_chunk_group(Frame& F, int bc, unsigned long long& tsub) {
;     ...
;             const float cr = bf2f(raw[tt + 1][0]), ck = bf2f(raw[tt + 1][1]), cv = bf2f(raw[tt + 1][2]);
;             const float r = cr + (pr - cr) * mur, k = ck + (pk - ck) * muk, v = cv + (pv - cv) * muv; pr = cr; pk = ck; pv = cv;
;             const float wl = *(const LAS float*)(L + L_WL + (t * 65 + ch) * 4), al = *(const LAS float*)(L + L_AL + (t * 65 + ch) * 4), gl = *(const LAS float*)(L + L_GL + (t * 65 + ch) * 4);
;             const float z = -(w0 + wl); const float sp = fmaxf(z, 0.f) + __logf(1.f + __expf(-fabsf(z)));
;             const float lgd = -__expf(-sp - 0.5f);
	v_mov_b32_e32 v103, v231
	v_lshlrev_b32_e32 v36, 16, v153
	v_lshlrev_b32_e32 v37, 16, v154
	v_sub_f32_e32 v36, v36, v37
	v_add_u32_e32 v38, s6, v119
	v_add_u32_e32 v39, s7, v119
	ds_read_b32 v38, v38
	ds_read_b32 v47, v39
	ds_read_b32 v177, v41
	ds_read_b32 v185, v87
	ds_read_b32 v191, v191
	v_lshlrev_b32_e32 v90, 16, v168
	v_and_b32_e32 v85, 0xffff0000, v169
	ds_read_b32 v182, v83
	ds_read_b32 v96, v96
	ds_read_b32 v189, v93
	ds_read_b32 v193, v97
	ds_read_b32 v194, v192
	s_waitcnt vmcnt(7)
	v_fma_f32 v173, v36, v95, v37
	v_add_u32_e32 v36, s33, v119
	ds_read_b32 v36, v36
	s_waitcnt vmcnt(4) lgkmcnt(0)
	v_add_f32_e32 v36, v45, v36
	v_max_f32_e64 v39, -v36, 0
	v_mul_f32_e64 v36, |v36|, s1
	v_exp_f32_e32 v36, v36
	s_nop 0
	v_add_f32_e32 v36, 1.0, v36

; __device__ __forceinline__ void rwkv_chunk_group(Frame& F, int bc, unsigned long long& tsub) {
;     ...
;             const float z = -(w0 + wl); const float sp = fmaxf(z, 0.f) + __logf(1.f + __expf(-fabsf(z)));
	s_nop 1


; __device__ __forceinline__ void rwkv_chunk_group(Frame& F, int bc, unsigned long long& tsub) {
;     ...
;             const float z = -(w0 + wl); const float sp = fmaxf(z, 0.f) + __logf(1.f + __expf(-fabsf(z)));
	v_log_f32_e32 v36, v36
	s_nop 0
	v_mul_f32_e32 v40, 0x3f317217, v36
	v_fma_f32 v40, v36, s9, -v40
	v_fmac_f32_e32 v40, 0x3377d1cf, v36
	v_fmac_f32_e32 v40, 0x3f317217, v36

; __device__ __forceinline__ void rwkv_chunk_group(Frame& F, int bc, unsigned long long& tsub) {
;     ...
;             const float z = -(w0 + wl); const float sp = fmaxf(z, 0.f) + __logf(1.f + __expf(-fabsf(z)));
	s_nop 1
	v_mov_b32_e32 v36, v40


; __device__ __forceinline__ float sigmoidf_(float x) { return __builtin_amdgcn_rcpf(1.0f + __expf(-x)); }
; __device__ __forceinline__ void rwkv_chunk_group(Frame& F, int bc, unsigned long long& tsub) {
;     ...
;             const float z = -(w0 + wl); const float sp = fmaxf(z, 0.f) + __logf(1.f + __expf(-fabsf(z)));
;             const float lgd = -__expf(-sp - 0.5f);
;             const float ic = sigmoidf_(a0 + al);
;             const float kv = k * k_k; const float kq = k * (1.f + (ic - 1.f) * k_a);
;             kkv[tt] = kv; icv[tt] = ic; sq[tt] = kv * kv; bq[tt] = r * kq * r_k;
;             rr[tt] = r; kp[tt] = kq; vv[tt] = v; run += lgd; ld[tt] = run; ggv[tt] = gl;
	v_add_f32_e32 v36, v39, v36
	v_add_u32_e32 v39, s33, v120
	ds_read_b32 v39, v39
	v_sub_f32_e32 v36, -0.5, v36
	v_mul_f32_e32 v36, 0x3fb8aa3b, v36
	v_exp_f32_e32 v102, v36
	s_waitcnt vmcnt(3)
	v_add_f32_e32 v36, v43, v38
	v_mul_f32_e32 v36, 0xbfb8aa3b, v36
	v_add_u32_e32 v40, s6, v120
	v_exp_f32_e32 v36, v36
	ds_read_b32 v40, v40
	s_waitcnt lgkmcnt(1)
	v_add_f32_e32 v39, v45, v39
	v_max_f32_e64 v41, -v39, 0
	v_mul_f32_e64 v39, |v39|, s1
	v_exp_f32_e32 v39, v39
	v_add_f32_e32 v36, 1.0, v36
	v_rcp_f32_e32 v38, v36
	v_sub_f32_e32 v36, v37, v82
	v_fma_f32 v174, v36, v95, v82
	v_and_b32_e32 v37, 0xffff0000, v161
	v_lshlrev_b32_e32 v36, 16, v161
	v_add_f32_e32 v39, 1.0, v39
	v_pk_add_f32 v[36:37], v[36:37], v[76:77] neg_lo:[0,1] neg_hi:[0,1]

; #define LAS __attribute__((address_space(3)))
; __device__ __forceinline__ void rwkv_chunk_group(Frame& F, int bc, unsigned long long& tsub) {
;     ...
;             const float r = cr + (pr - cr) * mur, k = ck + (pk - ck) * muk, v = cv + (pv - cv) * muv; pr = cr; pk = ck; pv = cv;
;             const float wl = *(const LAS float*)(L + L_WL + (t * 65 + ch) * 4), al = *(const LAS float*)(L + L_AL + (t * 65 + ch) * 4), gl = *(const LAS float*)(L + L_GL + (t * 65 + ch) * 4);
;             const float z = -(w0 + wl); const float sp = fmaxf(z, 0.f) + __logf(1.f + __expf(-fabsf(z)));
	v_pk_fma_f32 v[36:37], v[36:37], v[52:53], v[76:77] op_sel_hi:[1,0,1]
	s_nop 0


; __device__ __forceinline__ void rwkv_chunk_group(Frame& F, int bc, unsigned long long& tsub) {
;     ...
;             const float z = -(w0 + wl); const float sp = fmaxf(z, 0.f) + __logf(1.f + __expf(-fabsf(z)));
	v_log_f32_e32 v39, v39
	s_nop 0
	v_mul_f32_e32 v76, 0x3f317217, v39
	v_fma_f32 v76, v39, s9, -v76
	v_fmac_f32_e32 v76, 0x3377d1cf, v39
	v_fmac_f32_e32 v76, 0x3f317217, v39

; __device__ __forceinline__ void rwkv_chunk_group(Frame& F, int bc, unsigned long long& tsub) {
;     ...
;             const float z = -(w0 + wl); const float sp = fmaxf(z, 0.f) + __logf(1.f + __expf(-fabsf(z)));
	s_nop 1
	v_mov_b32_e32 v39, v76


; __device__ __forceinline__ float sigmoidf_(float x) { return __builtin_amdgcn_rcpf(1.0f + __expf(-x)); }
; __device__ __forceinline__ void rwkv_chunk_group(Frame& F, int bc, unsigned long long& tsub) {
;     ...
;             const float z = -(w0 + wl); const float sp = fmaxf(z, 0.f) + __logf(1.f + __expf(-fabsf(z)));
;             const float lgd = -__expf(-sp - 0.5f);
;             const float ic = sigmoidf_(a0 + al);
;             const float kv = k * k_k; const float kq = k * (1.f + (ic - 1.f) * k_a);
;             kkv[tt] = kv; icv[tt] = ic; sq[tt] = kv * kv; bq[tt] = r * kq * r_k;
;             rr[tt] = r; kp[tt] = kq; vv[tt] = v; run += lgd; ld[tt] = run; ggv[tt] = gl;
	v_add_f32_e32 v39, v41, v39
	v_sub_f32_e32 v39, -0.5, v39
	v_mul_f32_e32 v39, 0x3fb8aa3b, v39
	v_exp_f32_e32 v76, v39
	s_waitcnt lgkmcnt(0)
	v_add_f32_e32 v39, v43, v40
	v_mul_f32_e32 v39, 0xbfb8aa3b, v39
	v_exp_f32_e32 v39, v39
	v_and_b32_e32 v41, 0xffff0000, v160
	v_lshlrev_b32_e32 v40, 16, v160
	v_pk_add_f32 v[40:41], v[40:41], v[78:79] neg_lo:[0,1] neg_hi:[0,1]
	v_add_f32_e32 v39, 1.0, v39
	v_rcp_f32_e32 v39, v39
	v_pk_fma_f32 v[80:81], v[40:41], v[42:43], v[78:79] op_sel_hi:[1,0,1]
	v_sub_f32_e64 v176, -v102, v76
	v_lshlrev_b32_e32 v76, 16, v156
	v_pk_add_f32 v[40:41], v[38:39], -1.0 op_sel_hi:[1,0]
	s_waitcnt vmcnt(1)
	v_pk_fma_f32 v[40:41], v[46:47], v[40:41], 1.0 op_sel_hi:[0,1,0]
	v_pk_mul_f32 v[40:41], v[80:81], v[40:41]
	s_nop 0
	v_mul_f32_e32 v78, v173, v40
	s_waitcnt vmcnt(0)
	v_mul_f32_e32 v101, v103, v78
	v_mul_f32_e32 v78, v174, v41
	v_mul_f32_e32 v100, v103, v78
	v_sub_f32_e32 v78, v82, v76
	v_fma_f32 v175, v78, v95, v76
	v_add_u32_e32 v78, s33, v121
	ds_read_b32 v78, v78
	v_add_u32_e32 v82, s6, v121
	ds_read_b32 v82, v82
	v_sub_f32_e32 v76, v76, v86
	v_fma_f32 v178, v76, v95, v86
	s_waitcnt lgkmcnt(1)
	v_add_f32_e32 v78, v45, v78
	v_max_f32_e64 v83, -v78, 0
	v_mul_f32_e64 v78, |v78|, s1
	v_exp_f32_e32 v78, v78
	s_waitcnt lgkmcnt(0)
	v_add_f32_e32 v82, v43, v82
	v_mul_f32_e32 v82, 0xbfb8aa3b, v82
	v_exp_f32_e32 v82, v82
	v_add_f32_e32 v78, 1.0, v78

; __device__ __forceinline__ void rwkv_chunk_group(Frame& F, int bc, unsigned long long& tsub) {
;     ...
;             const float z = -(w0 + wl); const float sp = fmaxf(z, 0.f) + __logf(1.f + __expf(-fabsf(z)));
	v_add_f32_e32 v82, 1.0, v82
	s_nop 0


; __device__ __forceinline__ void rwkv_chunk_group(Frame& F, int bc, unsigned long long& tsub) {
;     ...
;             const float z = -(w0 + wl); const float sp = fmaxf(z, 0.f) + __logf(1.f + __expf(-fabsf(z)));
	v_log_f32_e32 v78, v78
	v_rcp_f32_e32 v82, v82
	v_mul_f32_e32 v84, 0x3f317217, v78
	v_fma_f32 v84, v78, s9, -v84
	v_fmac_f32_e32 v84, 0x3377d1cf, v78
	v_fmac_f32_e32 v84, 0x3f317217, v78

; __device__ __forceinline__ void rwkv_chunk_group(Frame& F, int bc, unsigned long long& tsub) {
;     ...
;             const float z = -(w0 + wl); const float sp = fmaxf(z, 0.f) + __logf(1.f + __expf(-fabsf(z)));
	s_nop 1
	v_mov_b32_e32 v78, v84


; #define LAS __attribute__((address_space(3)))
; __device__ __forceinline__ float sigmoidf_(float x) { return __builtin_amdgcn_rcpf(1.0f + __expf(-x)); }
; __device__ __forceinline__ void rwkv_chunk_group(Frame& F, int bc, unsigned long long& tsub) {
;     ...
;             const float r = cr + (pr - cr) * mur, k = ck + (pk - ck) * muk, v = cv + (pv - cv) * muv; pr = cr; pk = ck; pv = cv;
;             const float wl = *(const LAS float*)(L + L_WL + (t * 65 + ch) * 4), al = *(const LAS float*)(L + L_AL + (t * 65 + ch) * 4), gl = *(const LAS float*)(L + L_GL + (t * 65 + ch) * 4);
;             const float z = -(w0 + wl); const float sp = fmaxf(z, 0.f) + __logf(1.f + __expf(-fabsf(z)));
;             const float lgd = -__expf(-sp - 0.5f);
;             const float ic = sigmoidf_(a0 + al);
;             const float kv = k * k_k; const float kq = k * (1.f + (ic - 1.f) * k_a);
;             kkv[tt] = kv; icv[tt] = ic; sq[tt] = kv * kv; bq[tt] = r * kq * r_k;
;             rr[tt] = r; kp[tt] = kq; vv[tt] = v; run += lgd; ld[tt] = run; ggv[tt] = gl;
	v_add_f32_e32 v78, v83, v78
	v_sub_f32_e32 v78, -0.5, v78
	v_mul_f32_e32 v78, 0x3fb8aa3b, v78
	v_exp_f32_e32 v78, v78
	v_add_u32_e32 v83, s6, v122
	ds_read_b32 v83, v83
	v_lshlrev_b32_e32 v84, 16, v169
	v_sub_f32_e32 v179, v176, v78
	v_add_u32_e32 v78, s33, v122
	ds_read_b32 v78, v78
	v_pk_mov_b32 v[76:77], v[76:77], v[84:85] op_sel:[1,0]
	s_waitcnt lgkmcnt(0)
	v_add_f32_e32 v78, v45, v78
	v_max_f32_e64 v87, -v78, 0
	v_mul_f32_e64 v78, |v78|, s1
	v_exp_f32_e32 v78, v78
	v_pk_add_f32 v[76:77], v[76:77], v[84:85] neg_lo:[0,1] neg_hi:[0,1]
	v_add_f32_e32 v78, 1.0, v78

; __device__ __forceinline__ void rwkv_chunk_group(Frame& F, int bc, unsigned long long& tsub) {
;     ...
;             const float z = -(w0 + wl); const float sp = fmaxf(z, 0.f) + __logf(1.f + __expf(-fabsf(z)));
	v_pk_fma_f32 v[76:77], v[76:77], v[52:53], v[84:85] op_sel_hi:[1,0,1]
	s_nop 0


; __device__ __forceinline__ void rwkv_chunk_group(Frame& F, int bc, unsigned long long& tsub) {
;     ...
;             const float z = -(w0 + wl); const float sp = fmaxf(z, 0.f) + __logf(1.f + __expf(-fabsf(z)));
	v_log_f32_e32 v78, v78
	s_nop 0
	v_mul_f32_e32 v88, 0x3f317217, v78
	v_fma_f32 v88, v78, s9, -v88
	v_fmac_f32_e32 v88, 0x3377d1cf, v78
	v_fmac_f32_e32 v88, 0x3f317217, v78

; __device__ __forceinline__ void rwkv_chunk_group(Frame& F, int bc, unsigned long long& tsub) {
;     ...
;             const float z = -(w0 + wl); const float sp = fmaxf(z, 0.f) + __logf(1.f + __expf(-fabsf(z)));
	s_nop 1
	v_mov_b32_e32 v78, v88


; #define LAS __attribute__((address_space(3)))
; __device__ __forceinline__ float sigmoidf_(float x) { return __builtin_amdgcn_rcpf(1.0f + __expf(-x)); }
; __device__ __forceinline__ void rwkv_chunk_group(Frame& F, int bc, unsigned long long& tsub) {
;     ...
;             const float r = cr + (pr - cr) * mur, k = ck + (pk - ck) * muk, v = cv + (pv - cv) * muv; pr = cr; pk = ck; pv = cv;
;             const float wl = *(const LAS float*)(L + L_WL + (t * 65 + ch) * 4), al = *(const LAS float*)(L + L_AL + (t * 65 + ch) * 4), gl = *(const LAS float*)(L + L_GL + (t * 65 + ch) * 4);
;             const float z = -(w0 + wl); const float sp = fmaxf(z, 0.f) + __logf(1.f + __expf(-fabsf(z)));
;             const float lgd = -__expf(-sp - 0.5f);
;             const float ic = sigmoidf_(a0 + al);
;             const float kv = k * k_k; const float kq = k * (1.f + (ic - 1.f) * k_a);
;             kkv[tt] = kv; icv[tt] = ic; sq[tt] = kv * kv; bq[tt] = r * kq * r_k;
;             rr[tt] = r; kp[tt] = kq; vv[tt] = v; run += lgd; ld[tt] = run; ggv[tt] = gl;
	v_add_f32_e32 v78, v87, v78
	v_sub_f32_e32 v78, -0.5, v78
	v_mul_f32_e32 v78, 0x3fb8aa3b, v78
	v_exp_f32_e32 v87, v78
	v_add_f32_e32 v78, v43, v83
	v_mul_f32_e32 v78, 0xbfb8aa3b, v78
	v_exp_f32_e32 v78, v78
	v_sub_f32_e32 v181, v179, v87
	v_lshlrev_b32_e32 v87, 16, v158
	v_sub_f32_e32 v86, v86, v87
	v_add_f32_e32 v78, 1.0, v78
	v_rcp_f32_e32 v83, v78
	v_pk_mov_b32 v[78:79], v[78:79], v[90:91] op_sel:[1,0]
	v_fma_f32 v180, v86, v95, v87
	v_pk_add_f32 v[78:79], v[78:79], v[90:91] neg_lo:[0,1] neg_hi:[0,1]
	v_add_u32_e32 v86, s33, v123
	v_pk_fma_f32 v[88:89], v[78:79], v[42:43], v[90:91] op_sel_hi:[1,0,1]
	v_pk_add_f32 v[78:79], v[82:83], -1.0 op_sel_hi:[1,0]
	ds_read_b32 v86, v86
	v_pk_fma_f32 v[78:79], v[46:47], v[78:79], 1.0 op_sel_hi:[0,1,0]
	v_pk_mul_f32 v[78:79], v[88:89], v[78:79]
	s_nop 0
	v_mul_f32_e32 v92, v175, v78
	v_mul_f32_e32 v187, v103, v92
	v_mul_f32_e32 v92, v178, v79
	v_mul_f32_e32 v186, v103, v92
	v_add_u32_e32 v92, s6, v123
	ds_read_b32 v92, v92
	s_waitcnt lgkmcnt(1)
	v_add_f32_e32 v86, v45, v86
	v_max_f32_e64 v93, -v86, 0
	v_mul_f32_e64 v86, |v86|, s1
	v_exp_f32_e32 v86, v86
	s_nop 0
	v_add_f32_e32 v86, 1.0, v86

; __device__ __forceinline__ void rwkv_chunk_group(Frame& F, int bc, unsigned long long& tsub) {
;     ...
;             const float z = -(w0 + wl); const float sp = fmaxf(z, 0.f) + __logf(1.f + __expf(-fabsf(z)));
	s_nop 1


; __device__ __forceinline__ void rwkv_chunk_group(Frame& F, int bc, unsigned long long& tsub) {
;     ...
;             const float z = -(w0 + wl); const float sp = fmaxf(z, 0.f) + __logf(1.f + __expf(-fabsf(z)));
	v_log_f32_e32 v86, v86
	s_nop 0
	v_mul_f32_e32 v94, 0x3f317217, v86
	v_fma_f32 v94, v86, s9, -v94
	v_fmac_f32_e32 v94, 0x3377d1cf, v86
	v_fmac_f32_e32 v94, 0x3f317217, v86

; __device__ __forceinline__ void rwkv_chunk_group(Frame& F, int bc, unsigned long long& tsub) {
;     ...
;             const float z = -(w0 + wl); const float sp = fmaxf(z, 0.f) + __logf(1.f + __expf(-fabsf(z)));
	s_nop 1
	v_mov_b32_e32 v86, v94


; #define LAS __attribute__((address_space(3)))
; __device__ __forceinline__ float sigmoidf_(float x) { return __builtin_amdgcn_rcpf(1.0f + __expf(-x)); }
; __device__ __forceinline__ void rwkv_chunk_group(Frame& F, int bc, unsigned long long& tsub) {
;     ...
;             const float r = cr + (pr - cr) * mur, k = ck + (pk - ck) * muk, v = cv + (pv - cv) * muv; pr = cr; pk = ck; pv = cv;
;             const float wl = *(const LAS float*)(L + L_WL + (t * 65 + ch) * 4), al = *(const LAS float*)(L + L_AL + (t * 65 + ch) * 4), gl = *(const LAS float*)(L + L_GL + (t * 65 + ch) * 4);
;             const float z = -(w0 + wl); const float sp = fmaxf(z, 0.f) + __logf(1.f + __expf(-fabsf(z)));
;             const float lgd = -__expf(-sp - 0.5f);
;             const float ic = sigmoidf_(a0 + al);
;             const float kv = k * k_k; const float kq = k * (1.f + (ic - 1.f) * k_a);
;             kkv[tt] = kv; icv[tt] = ic; sq[tt] = kv * kv; bq[tt] = r * kq * r_k;
;             rr[tt] = r; kp[tt] = kq; vv[tt] = v; run += lgd; ld[tt] = run; ggv[tt] = gl;
	v_lshlrev_b32_e32 v94, 16, v159
	v_sub_f32_e32 v87, v87, v94
	v_fma_f32 v183, v87, v95, v94
	v_add_u32_e32 v87, s33, v124
	ds_read_b32 v87, v87
	v_add_f32_e32 v86, v93, v86
	v_sub_f32_e32 v86, -0.5, v86
	v_mul_f32_e32 v86, 0x3fb8aa3b, v86
	v_exp_f32_e32 v93, v86
	s_waitcnt lgkmcnt(0)
	v_add_f32_e32 v87, v45, v87
	v_max_f32_e64 v97, -v87, 0
	v_mul_f32_e64 v87, |v87|, s1
	v_exp_f32_e32 v87, v87
	v_add_f32_e32 v86, v43, v92
	v_mul_f32_e32 v86, 0xbfb8aa3b, v86
	v_exp_f32_e32 v86, v86
	v_add_f32_e32 v87, 1.0, v87

; __device__ __forceinline__ float sigmoidf_(float x) { return __builtin_amdgcn_rcpf(1.0f + __expf(-x)); }
; __device__ __forceinline__ void rwkv_chunk_group(Frame& F, int bc, unsigned long long& tsub) {
;     ...
;             const float z = -(w0 + wl); const float sp = fmaxf(z, 0.f) + __logf(1.f + __expf(-fabsf(z)));
;             const float lgd = -__expf(-sp - 0.5f);
;             const float ic = sigmoidf_(a0 + al);
;             const float kv = k * k_k; const float kq = k * (1.f + (ic - 1.f) * k_a);
;             kkv[tt] = kv; icv[tt] = ic; sq[tt] = kv * kv; bq[tt] = r * kq * r_k;
;             rr[tt] = r; kp[tt] = kq; vv[tt] = v; run += lgd; ld[tt] = run; ggv[tt] = gl;
	v_sub_f32_e32 v184, v181, v93
	v_add_f32_e32 v86, 1.0, v86


; __device__ __forceinline__ void rwkv_chunk_group(Frame& F, int bc, unsigned long long& tsub) {
;     ...
;             const float z = -(w0 + wl); const float sp = fmaxf(z, 0.f) + __logf(1.f + __expf(-fabsf(z)));
	v_log_f32_e32 v87, v87
	v_rcp_f32_e32 v86, v86
	v_sub_f32_e32 v94, v94, v197
	v_and_b32_e32 v93, 0xffff0000, v171
	v_mul_f32_e32 v98, 0x3f317217, v87
	v_fma_f32 v98, v87, s9, -v98
	v_fmac_f32_e32 v98, 0x3377d1cf, v87
	v_fmac_f32_e32 v98, 0x3f317217, v87

; __device__ __forceinline__ void rwkv_chunk_group(Frame& F, int bc, unsigned long long& tsub) {
;     ...
;             const float z = -(w0 + wl); const float sp = fmaxf(z, 0.f) + __logf(1.f + __expf(-fabsf(z)));
	v_lshlrev_b32_e32 v92, 16, v171
	v_pk_mov_b32 v[84:85], v[84:85], v[92:93] op_sel:[1,0]
	v_mov_b32_e32 v87, v98


; #define LAS __attribute__((address_space(3)))
; __device__ __forceinline__ float sigmoidf_(float x) { return __builtin_amdgcn_rcpf(1.0f + __expf(-x)); }
; __device__ __forceinline__ void rwkv_chunk_group(Frame& F, int bc, unsigned long long& tsub) {
;     ...
;             const float r = cr + (pr - cr) * mur, k = ck + (pk - ck) * muk, v = cv + (pv - cv) * muv; pr = cr; pk = ck; pv = cv;
;             const float wl = *(const LAS float*)(L + L_WL + (t * 65 + ch) * 4), al = *(const LAS float*)(L + L_AL + (t * 65 + ch) * 4), gl = *(const LAS float*)(L + L_GL + (t * 65 + ch) * 4);
;             const float z = -(w0 + wl); const float sp = fmaxf(z, 0.f) + __logf(1.f + __expf(-fabsf(z)));
;             const float lgd = -__expf(-sp - 0.5f);
;             const float ic = sigmoidf_(a0 + al);
;             const float kv = k * k_k; const float kq = k * (1.f + (ic - 1.f) * k_a);
;             kkv[tt] = kv; icv[tt] = ic; sq[tt] = kv * kv; bq[tt] = r * kq * r_k;
;             rr[tt] = r; kp[tt] = kq; vv[tt] = v; run += lgd; ld[tt] = run; ggv[tt] = gl;
;         }
;         wave_sum8(sq); wave_sum8(bq);
	v_add_f32_e32 v87, v97, v87
	v_sub_f32_e32 v87, -0.5, v87
	v_mul_f32_e32 v87, 0x3fb8aa3b, v87
	v_exp_f32_e32 v188, v87
	v_add_f32_e32 v87, v43, v96
	v_mul_f32_e32 v87, 0xbfb8aa3b, v87
	v_exp_f32_e32 v87, v87
	v_and_b32_e32 v97, 0xffff0000, v170
	v_lshlrev_b32_e32 v96, 16, v170
	v_pk_mov_b32 v[90:91], v[90:91], v[96:97] op_sel:[1,0]
	v_add_f32_e32 v87, 1.0, v87
	v_rcp_f32_e32 v87, v87
	v_pk_add_f32 v[90:91], v[90:91], v[96:97] neg_lo:[0,1] neg_hi:[0,1]
	v_pk_add_f32 v[84:85], v[84:85], v[92:93] neg_lo:[0,1] neg_hi:[0,1]
	v_pk_fma_f32 v[98:99], v[90:91], v[42:43], v[96:97] op_sel_hi:[1,0,1]
	v_pk_add_f32 v[90:91], v[86:87], -1.0 op_sel_hi:[1,0]
	v_pk_fma_f32 v[84:85], v[84:85], v[52:53], v[92:93] op_sel_hi:[1,0,1]
	v_pk_fma_f32 v[90:91], v[46:47], v[90:91], 1.0 op_sel_hi:[0,1,0]
	v_pk_mul_f32 v[90:91], v[98:99], v[90:91]
	s_nop 0
	v_mul_f32_e32 v190, v180, v90
	v_mul_f32_e32 v196, v103, v190
	v_mul_f32_e32 v190, v183, v91
	v_mul_f32_e32 v195, v103, v190
	v_sub_f32_e32 v190, v184, v188
	v_fma_f32 v188, v94, v95, v197
	v_add_u32_e32 v94, s33, v125
	ds_read_b32 v94, v94
	v_permlane32_swap_b32_e32 v101, v196
	v_permlane32_swap_b32_e32 v100, v195
	s_waitcnt lgkmcnt(0)
	v_add_f32_e32 v94, v45, v94
	v_max_f32_e64 v192, -v94, 0
	v_mul_f32_e64 v94, |v94|, s1
	v_exp_f32_e32 v94, v94
	v_add_f32_e32 v201, v101, v196
	v_add_f32_e32 v195, v100, v195
	v_add_f32_e32 v94, 1.0, v94

; __device__ __forceinline__ void rwkv_chunk_group(Frame& F, int bc, unsigned long long& tsub) {
;     ...
;             const float z = -(w0 + wl); const float sp = fmaxf(z, 0.f) + __logf(1.f + __expf(-fabsf(z)));
	s_nop 1


; __device__ __forceinline__ void rwkv_chunk_group(Frame& F, int bc, unsigned long long& tsub) {
;     ...
;             const float z = -(w0 + wl); const float sp = fmaxf(z, 0.f) + __logf(1.f + __expf(-fabsf(z)));
	v_log_f32_e32 v94, v94
	s_nop 0
	v_mul_f32_e32 v198, 0x3f317217, v94
	v_fma_f32 v198, v94, s9, -v198
	v_fmac_f32_e32 v198, 0x3377d1cf, v94
	v_fmac_f32_e32 v198, 0x3f317217, v94

; __device__ __forceinline__ void rwkv_chunk_group(Frame& F, int bc, unsigned long long& tsub) {
;     ...
;             const float z = -(w0 + wl); const float sp = fmaxf(z, 0.f) + __logf(1.f + __expf(-fabsf(z)));
	s_nop 1
	v_mov_b32_e32 v94, v198


; #define LAS __attribute__((address_space(3)))
; __device__ __forceinline__ float sigmoidf_(float x) { return __builtin_amdgcn_rcpf(1.0f + __expf(-x)); }
; __device__ __forceinline__ void rwkv_chunk_group(Frame& F, int bc, unsigned long long& tsub) {
;     ...
;             const float r = cr + (pr - cr) * mur, k = ck + (pk - ck) * muk, v = cv + (pv - cv) * muv; pr = cr; pk = ck; pv = cv;
;             const float wl = *(const LAS float*)(L + L_WL + (t * 65 + ch) * 4), al = *(const LAS float*)(L + L_AL + (t * 65 + ch) * 4), gl = *(const LAS float*)(L + L_GL + (t * 65 + ch) * 4);
;             const float z = -(w0 + wl); const float sp = fmaxf(z, 0.f) + __logf(1.f + __expf(-fabsf(z)));
;             const float lgd = -__expf(-sp - 0.5f);
;             const float ic = sigmoidf_(a0 + al);
	v_lshlrev_b32_e32 v198, 16, v172
	v_pk_mov_b32 v[92:93], v[92:93], v[198:199] op_sel:[1,0]
	v_add_f32_e32 v94, v192, v94
	v_pk_add_f32 v[92:93], v[92:93], v[198:199] neg_lo:[0,1] neg_hi:[0,1]
	v_sub_f32_e32 v94, -0.5, v94
	v_pk_fma_f32 v[92:93], v[92:93], v[52:53], v[198:199] op_sel_hi:[1,0,1]
	v_add_u32_e32 v52, s33, v126
	ds_read_b32 v52, v52
	v_mul_f32_e32 v94, 0x3fb8aa3b, v94
	v_exp_f32_e32 v192, v94
	v_add_f32_e32 v94, v43, v191
	v_lshlrev_b32_e32 v191, 16, v163
	v_sub_f32_e32 v197, v197, v191
	v_fmac_f32_e32 v191, v197, v95
	v_add_u32_e32 v95, s6, v126
	v_add_u32_e32 v197, s7, v126
	ds_read_b32 v95, v95
	ds_read_b32 v200, v197
	s_waitcnt lgkmcnt(2)
	v_add_f32_e32 v45, v45, v52
	v_max_f32_e64 v52, -v45, 0
	v_mul_f32_e64 v45, |v45|, s1
	v_exp_f32_e32 v45, v45
	s_waitcnt lgkmcnt(1)
	v_add_f32_e32 v43, v43, v95
	v_mul_f32_e32 v94, 0xbfb8aa3b, v94
	v_mul_f32_e32 v43, 0xbfb8aa3b, v43
	v_add_f32_e32 v45, 1.0, v45

; __device__ __forceinline__ float sigmoidf_(float x) { return __builtin_amdgcn_rcpf(1.0f + __expf(-x)); }
; __device__ __forceinline__ void rwkv_chunk_group(Frame& F, int bc, unsigned long long& tsub) {
;     ...
;             const float z = -(w0 + wl); const float sp = fmaxf(z, 0.f) + __logf(1.f + __expf(-fabsf(z)));
;             const float lgd = -__expf(-sp - 0.5f);
;             const float ic = sigmoidf_(a0 + al);
	v_exp_f32_e32 v94, v94
	v_exp_f32_e32 v43, v43


; __device__ __forceinline__ float sigmoidf_(float x) { return __builtin_amdgcn_rcpf(1.0f + __expf(-x)); }
; __device__ __forceinline__ void rwkv_chunk_group(Frame& F, int bc, unsigned long long& tsub) {
;     ...
;             const float z = -(w0 + wl); const float sp = fmaxf(z, 0.f) + __logf(1.f + __expf(-fabsf(z)));
;             const float lgd = -__expf(-sp - 0.5f);
;             const float ic = sigmoidf_(a0 + al);
	v_log_f32_e32 v45, v45
	v_add_f32_e32 v94, 1.0, v94
	v_add_f32_e32 v43, 1.0, v43
	v_rcp_f32_e32 v94, v94
	v_mul_f32_e32 v197, 0x3f317217, v45
	v_fma_f32 v197, v45, s9, -v197
	v_fmac_f32_e32 v197, 0x3377d1cf, v45
	v_fmac_f32_e32 v197, 0x3f317217, v45

; __device__ __forceinline__ float sigmoidf_(float x) { return __builtin_amdgcn_rcpf(1.0f + __expf(-x)); }
; __device__ __forceinline__ void rwkv_chunk_group(Frame& F, int bc, unsigned long long& tsub) {
;     ...
;             const float z = -(w0 + wl); const float sp = fmaxf(z, 0.f) + __logf(1.f + __expf(-fabsf(z)));
;             const float lgd = -__expf(-sp - 0.5f);
;             const float ic = sigmoidf_(a0 + al);
;             const float kv = k * k_k; const float kq = k * (1.f + (ic - 1.f) * k_a);
;             kkv[tt] = kv; icv[tt] = ic; sq[tt] = kv * kv; bq[tt] = r * kq * r_k;
;             rr[tt] = r; kp[tt] = kq; vv[tt] = v; run += lgd; ld[tt] = run; ggv[tt] = gl;
	v_rcp_f32_e32 v95, v43
	v_sub_f32_e32 v192, v190, v192
	v_mov_b32_e32 v45, v197


; #define GAS __attribute__((address_space(1)))
; #define LAS __attribute__((address_space(3)))
; __device__ __forceinline__ unsigned pk2(float lo, float hi) { f32x2_k v = {lo, hi}; bf16x2_k b = __builtin_convertvector(v, bf16x2_k); return __builtin_bit_cast(unsigned, b); }
; __device__ __forceinline__ float sigmoidf_(float x) { return __builtin_amdgcn_rcpf(1.0f + __expf(-x)); }
; __device__ __forceinline__ void rwkv_chunk_group(Frame& F, int bc, unsigned long long& tsub) {
;     ...
;             const float z = -(w0 + wl); const float sp = fmaxf(z, 0.f) + __logf(1.f + __expf(-fabsf(z)));
;             const float lgd = -__expf(-sp - 0.5f);
;             const float ic = sigmoidf_(a0 + al);
;             const float kv = k * k_k; const float kq = k * (1.f + (ic - 1.f) * k_a);
;             kkv[tt] = kv; icv[tt] = ic; sq[tt] = kv * kv; bq[tt] = r * kq * r_k;
;             rr[tt] = r; kp[tt] = kq; vv[tt] = v; run += lgd; ld[tt] = run; ggv[tt] = gl;
;         }
;         wave_sum8(sq); wave_sum8(bq);
; #pragma unroll
;         for (int tt = 0; tt < 8; ++tt) { const float kn = kkv[tt] * __builtin_amdgcn_rsqf(fmaxf(sq[tt], 1e-24f));
;             aa[tt] = -kn; bb[tt] = kn * icv[tt]; vbv[tt] = bq[tt] * vv[tt]; }
;         *(LAS float*)(L + L_GT + (w * 64 + ch) * 4) = run;
;         *(GAS v4u*)(VBp + ch * 64 + tb) = (v4u){pk2(vbv[0], vbv[1]), pk2(vbv[2], vbv[3]), pk2(vbv[4], vbv[5]), pk2(vbv[6], vbv[7])};
;         *(GAS v4u*)(Gp + ch * 64 + tb) = (v4u){pk2(ggv[0], ggv[1]), pk2(ggv[2], ggv[3]), pk2(ggv[4], ggv[5]), pk2(ggv[6], ggv[7])};
;         if (hh + 1 < RW_H) {
;             const bool has = (c * CH + tb > 0);
; #pragma unroll
;             for (int tt = 0; tt < 9; ++tt) { const size_t off = (size_t)(row0 + tb + tt - 1) * PRW + hnext * 64 + ch;
;                 if (tt > 0 || has) { raw[tt][0] = P[off]; raw[tt][1] = P[off + 512]; raw[tt][2] = P[off + 1024]; } }
	v_add_f32_e32 v45, v52, v45
	v_sub_f32_e32 v45, -0.5, v45
	v_mul_f32_e32 v45, 0x3fb8aa3b, v45
	v_exp_f32_e32 v45, v45
	s_nop 0
	v_pk_mul_f32 v[100:101], v[80:81], v[44:45] op_sel_hi:[1,0]
	v_pk_mul_f32 v[80:81], v[98:99], v[44:45] op_sel_hi:[1,0]
	v_pk_mul_f32 v[196:197], v[100:101], v[100:101]
	v_pk_mul_f32 v[98:99], v[80:81], v[80:81]
	v_sub_f32_e32 v52, v192, v45
	s_nop 0
	v_permlane32_swap_b32_e32 v196, v98
	v_permlane32_swap_b32_e32 v197, v99
	v_add_f32_e32 v196, v196, v98
	v_add_f32_e32 v197, v197, v99
	v_lshlrev_b32_e32 v98, 16, v165
	v_and_b32_e32 v99, 0xffff0000, v165
	v_pk_mov_b32 v[96:97], v[96:97], v[98:99] op_sel:[1,0]
	v_pk_mul_f32 v[88:89], v[88:89], v[44:45] op_sel_hi:[1,0]
	v_pk_add_f32 v[96:97], v[96:97], v[98:99] neg_lo:[0,1] neg_hi:[0,1]
	v_pk_mul_f32 v[198:199], v[88:89], v[88:89]
	v_pk_fma_f32 v[42:43], v[96:97], v[42:43], v[98:99] op_sel_hi:[1,0,1]
	v_pk_add_f32 v[98:99], v[94:95], -1.0 op_sel_hi:[1,0]
	v_pk_mul_f32 v[44:45], v[42:43], v[44:45] op_sel_hi:[1,0]
	v_pk_fma_f32 v[98:99], v[46:47], v[98:99], 1.0 op_sel_hi:[0,1,0]
	v_pk_mul_f32 v[42:43], v[42:43], v[98:99]
	v_pk_mul_f32 v[96:97], v[44:45], v[44:45]
	v_mul_f32_e32 v46, v188, v42
	v_mul_f32_e32 v46, v103, v46
	s_nop 1
	v_permlane32_swap_b32_e32 v187, v46
	v_add_f32_e32 v46, v187, v46
	v_mul_f32_e32 v98, v191, v43
	s_nop 0
	v_permlane16_swap_b32_e32 v201, v46
	v_mul_f32_e32 v98, v103, v98
	v_add_f32_e32 v46, v201, v46
	s_nop 0
	v_permlane32_swap_b32_e32 v186, v98
	v_add_f32_dpp v46, v46, v46 quad_perm:[1,0,3,2] row_mask:0xf bank_mask:0xf bound_ctrl:1
	v_add_f32_e32 v98, v186, v98
	s_nop 1
	v_permlane16_swap_b32_e32 v195, v98
	v_add_f32_dpp v46, v46, v46 quad_perm:[2,3,0,1] row_mask:0xf bank_mask:0xf bound_ctrl:1
	v_add_f32_e32 v98, v195, v98
	v_permlane32_swap_b32_e32 v198, v96
	v_add_f32_dpp v46, v46, v46 row_half_mirror row_mask:0xf bank_mask:0xf bound_ctrl:1
	v_permlane32_swap_b32_e32 v199, v97
	s_nop 0
	v_add_f32_dpp v46, v46, v46 row_mirror row_mask:0xf bank_mask:0xf bound_ctrl:1
	v_add_f32_dpp v98, v98, v98 quad_perm:[1,0,3,2] row_mask:0xf bank_mask:0xf bound_ctrl:1
	v_readlane_b32 s14, v46, 0
	v_readlane_b32 s64, v46, 16
	v_readlane_b32 s72, v46, 32
	v_readlane_b32 s96, v46, 48
	v_add_f32_e32 v46, v198, v96
	v_add_f32_e32 v96, v199, v97
	v_add_f32_dpp v98, v98, v98 quad_perm:[2,3,0,1] row_mask:0xf bank_mask:0xf bound_ctrl:1
	v_permlane16_swap_b32_e32 v196, v46
	v_permlane16_swap_b32_e32 v197, v96
	v_add_f32_dpp v98, v98, v98 row_half_mirror row_mask:0xf bank_mask:0xf bound_ctrl:1
	v_add_f32_e32 v46, v196, v46
	v_add_f32_e32 v96, v197, v96
	v_add_f32_dpp v98, v98, v98 row_mirror row_mask:0xf bank_mask:0xf bound_ctrl:1
	v_add_f32_dpp v46, v46, v46 quad_perm:[1,0,3,2] row_mask:0xf bank_mask:0xf bound_ctrl:1
	v_add_f32_dpp v96, v96, v96 quad_perm:[1,0,3,2] row_mask:0xf bank_mask:0xf bound_ctrl:1
	v_readlane_b32 s73, v98, 32
	v_add_f32_dpp v46, v46, v46 quad_perm:[2,3,0,1] row_mask:0xf bank_mask:0xf bound_ctrl:1
	v_add_f32_dpp v96, v96, v96 quad_perm:[2,3,0,1] row_mask:0xf bank_mask:0xf bound_ctrl:1
	v_readlane_b32 s15, v98, 0
	v_readlane_b32 s65, v98, 16
	v_readlane_b32 s97, v98, 48
	v_add_f32_dpp v46, v46, v46 row_half_mirror row_mask:0xf bank_mask:0xf bound_ctrl:1
	v_add_f32_dpp v96, v96, v96 row_half_mirror row_mask:0xf bank_mask:0xf bound_ctrl:1
	v_pk_mul_f32 v[196:197], v[84:85], s[72:73]
	s_lshl_b64 s[72:73], s[66:67], 13
	v_pk_mul_f32 v[98:99], v[36:37], s[14:15]
	v_pk_mul_f32 v[186:187], v[76:77], s[64:65]
	v_add_f32_dpp v46, v46, v46 row_mirror row_mask:0xf bank_mask:0xf bound_ctrl:1
	v_add_f32_dpp v96, v96, v96 row_mirror row_mask:0xf bank_mask:0xf bound_ctrl:1
	v_pk_mul_f32 v[198:199], v[92:93], s[96:97]
	v_readlane_b32 s15, v254, 39
	s_cmp_eq_u32 s68, 7
	v_readlane_b32 s93, v46, 0
	v_readlane_b32 s71, v46, 16
	v_readlane_b32 s69, v46, 32
	v_readlane_b32 s64, v46, 48
	v_readlane_b32 s14, v96, 0
	v_readlane_b32 s77, v96, 16
	v_readlane_b32 s70, v96, 32
	v_readlane_b32 s65, v96, 48
	v_add_u32_e32 v46, s15, v105
	v_cvt_pk_bf16_f32 v96, v98, v99
	v_cvt_pk_bf16_f32 v97, v186, v187
	v_cvt_pk_bf16_f32 v98, v196, v197
	v_cvt_pk_bf16_f32 v99, v198, v199
	v_lshl_add_u64 v[186:187], v[62:63], 0, s[72:73]
	s_cselect_b64 s[96:97], -1, 0
	ds_write_b32 v46, v52
	global_store_dwordx4 v[186:187], v[96:99], off
	s_and_b64 vcc, exec, s[96:97]
	s_nop 0
	v_cvt_pk_bf16_f32 v96, v47, v177
	v_cvt_pk_bf16_f32 v97, v182, v185
	v_cvt_pk_bf16_f32 v98, v189, v193
	s_waitcnt lgkmcnt(1)
	v_cvt_pk_bf16_f32 v99, v194, v200
	v_lshl_add_u64 v[46:47], v[64:65], 0, s[72:73]
	global_store_dwordx4 v[46:47], v[96:99], off
	s_cbranch_vccnz .LBB0_1416
	v_readlane_b32 s72, v254, 60
	s_lshl_b32 s94, s13, 7
	v_readlane_b32 s73, v254, 61
	v_lshl_add_u64 v[46:47], v[56:57], 0, s[94:95]
	s_andn2_b64 vcc, exec, s[72:73]
	s_cbranch_vccnz .LBB0_1415
	v_readlane_b32 s72, v254, 62
	v_readlane_b32 s73, v254, 63
	s_nop 1
	v_lshl_add_u64 v[96:97], v[46:47], 0, s[72:73]
	global_load_ushort v153, v[96:97], off
	global_load_ushort v202, v[96:97], off offset:1024
	global_load_ushort v215, v[96:97], off offset:2048
